# v31
# baseline (speedup 1.0000x reference)
.LBB0_736:
	s_waitcnt lgkmcnt(0)
	s_add_u32 s22, s4, s20
	s_addc_u32 s23, s5, s21
	global_load_dwordx4 v[6:9], v209, s[22:23]
	s_add_u32 s22, s6, s20
	s_addc_u32 s23, s7, s21
	s_add_u32 s24, s8, s20
	s_addc_u32 s25, s9, s21
	global_load_dwordx4 v[10:13], v209, s[24:25]
	s_add_u32 s24, s10, s20
	s_addc_u32 s25, s11, s21
	global_load_dwordx4 v[14:17], v209, s[24:25]
	s_add_u32 s24, s16, s20
	s_addc_u32 s25, s17, s21
	global_load_dwordx4 v[18:21], v209, s[24:25]
	s_add_u32 s24, s18, s20
	s_addc_u32 s25, s19, s21
	global_load_dwordx4 v[22:25], v209, s[24:25]
	global_load_dwordx4 v[26:29], v209, s[22:23]
	s_add_u32 s20, s20, 16
	s_addc_u32 s21, s21, 0
	s_cmpk_eq_i32 s20, 0x100
	s_waitcnt vmcnt(5)
	v_max3_f32 v4, v4, |v6|, |v7|
	v_max3_f32 v4, v4, |v8|, |v9|
	s_waitcnt vmcnt(4)
	v_mov_b32_e32 v6, v10
	v_mov_b32_e32 v8, v12
	s_waitcnt vmcnt(3)
	v_mov_b32_e32 v10, v14
	v_mov_b32_e32 v12, v16
	s_waitcnt vmcnt(2)
	v_mov_b32_e32 v7, v18
	v_mov_b32_e32 v18, v11
	s_waitcnt vmcnt(1)
	v_mov_b32_e32 v11, v22
	v_mov_b32_e32 v22, v15
	v_pk_fma_f32 v[0:1], v[6:7], v[10:11], v[0:1]
	v_mov_b32_e32 v9, v20
	v_mov_b32_e32 v20, v13
	v_mov_b32_e32 v13, v24
	v_pk_fma_f32 v[0:1], v[18:19], v[22:23], v[0:1]
	s_waitcnt vmcnt(0)
	v_max3_f32 v3, v3, |v26|, |v27|
	v_mov_b32_e32 v24, v17
	v_pk_fma_f32 v[0:1], v[8:9], v[12:13], v[0:1]
	v_max3_f32 v3, v3, |v28|, |v29|
	v_pk_fma_f32 v[0:1], v[20:21], v[24:25], v[0:1]
	s_cbranch_scc0 .LBB0_736
	v_mul_f32_e32 v5, 0x3fb8aa3b, v0
	v_rndne_f32_e32 v6, v5
	s_mov_b32 s4, 0x3fb8aa3b
	v_sub_f32_e32 v7, v5, v6
	v_fma_f32 v5, v0, s4, -v5
	v_fmac_f32_e32 v5, 0x32a5705f, v0
	v_add_f32_e32 v5, v7, v5
	v_cvt_i32_f32_e32 v6, v6
	v_exp_f32_e32 v5, v5
	s_mov_b32 s5, 0x42b17218
	s_mov_b32 s53, s2
	v_ldexp_f32 v5, v5, v6
	v_mul_f32_e32 v6, 0x3fb8aa3b, v1
	v_rndne_f32_e32 v7, v6
	v_sub_f32_e32 v8, v6, v7
	v_fma_f32 v6, v1, s4, -v6
	v_fmac_f32_e32 v6, 0x32a5705f, v1
	v_add_f32_e32 v6, v8, v6
	v_exp_f32_e32 v6, v6
	v_cvt_i32_f32_e32 v7, v7
	s_mov_b32 s4, 0xc2ce8ed0
	v_cmp_ngt_f32_e32 vcc, s4, v0
	v_mov_b32_e32 v8, 0x7f800000
	s_cmpk_gt_i32 s53, 0xfff
	v_cndmask_b32_e32 v5, 0, v5, vcc
	v_cmp_nlt_f32_e32 vcc, s5, v0
	s_nop 1
	v_cndmask_b32_e32 v0, v8, v5, vcc
	v_ldexp_f32 v5, v6, v7
	v_cmp_ngt_f32_e32 vcc, s4, v1
	s_nop 1
	v_cndmask_b32_e32 v5, 0, v5, vcc
	v_cmp_nlt_f32_e32 vcc, s5, v1
	s_nop 1
	v_cndmask_b32_e32 v1, v8, v5, vcc
	v_sub_f32_e32 v0, v0, v1
	s_nop 0
	v_readfirstlane_b32 s5, v0
	v_mul_f32_e32 v0, 0x4138aa3b, v4
	v_mul_f32_e32 v0, v3, v0
	s_nop 0
	v_readfirstlane_b32 s4, v0
	s_cbranch_scc1 .LBB0_749
	s_add_u32 s8, s54, 0x22000000
	v_or_b32_e32 v0, s33, v2
	s_addc_u32 s9, s55, 0
	s_add_u32 s10, s54, 0x12000000
	v_mov_b32_e32 v1, 0x3eb60549
	s_load_dwordx2 s[34:35], s[0:1], 0xe8
	v_ashrrev_i32_e32 v5, 8, v0
	s_addc_u32 s11, s55, 0
	v_add_f32_e32 v145, s5, v1
	v_lshlrev_b32_e32 v148, 6, v5
	v_mul_i32_i24_e32 v168, 0x2400, v5
	s_xor_b32 s16, s4, 0x80000000
	v_cmp_eq_u32_e64 s[4:5], 1, v5
	s_movk_i32 s6, 0x100
	v_lshlrev_b32_e32 v5, 8, v0
	v_ashrrev_i32_e32 v147, 3, v0
	v_lshlrev_b32_e32 v1, 3, v0
	v_bfe_u32 v3, v0, 6, 2
	v_and_b32_e32 v4, 63, v2
	v_cmp_gt_u32_e64 s[6:7], s6, v0
	v_and_b32_e32 v8, 0xc000, v5
	v_lshlrev_b32_e32 v0, 4, v0
	v_and_b32_e32 v146, 56, v1
	v_and_b32_e32 v1, 31, v2
	v_bfe_u32 v6, v2, 5, 1
	v_lshlrev_b32_e32 v166, 5, v3
	v_lshl_add_u32 v4, v4, 2, 0
	v_add_u32_e32 v9, 0, v8
	v_and_b32_e32 v208, 0xf0, v0
	v_or_b32_e32 v167, v166, v1
	v_mul_u32_u24_e32 v169, 0x90, v1
	v_mul_u32_u24_e32 v10, 0x110, v1
	v_add_u32_e32 v11, v9, v208
	v_lshl_add_u64 v[0:1], s[54:55], 0, v[208:209]
	v_lshl_add_u32 v172, v3, 14, v4
	v_lshlrev_b32_e32 v208, 4, v6
	v_lshrrev_b32_e32 v3, 4, v2
	v_and_b32_e32 v151, 63, v147
	s_mov_b64 s[18:19], 0x2a000000
	s_waitcnt lgkmcnt(0)
	v_lshl_add_u64 v[154:155], s[34:35], 0, v[208:209]
	s_cmp_ge_u32 s33, 0x100
	s_cbranch_scc0 .Lprio_da
	s_setprio 1
.Lprio_da:
	v_and_b32_e32 v7, 31, v2
	v_lshlrev_b32_e32 v7, 4, v7
	global_load_dword v175, v7, s[34:35]
	global_load_dword v178, v7, s[34:35] offset:4
	global_load_dword v182, v7, s[34:35] offset:8
	global_load_dword v150, v7, s[34:35] offset:12
	v_add_u32_e32 v7, 0x1f000, v7
	v_add_u32_e32 v154, 0x1f000, v208
	s_waitcnt vmcnt(0)
	ds_write_b32 v7, v175
	ds_write_b32 v7, v178 offset:4
	ds_write_b32 v7, v182 offset:8
	ds_write_b32 v7, v150 offset:12
	s_waitcnt lgkmcnt(0)
	s_barrier
	v_bfe_u32 v175, v2, 4, 2
	v_or_b32_e32 v178, 12, v3
	s_movk_i32 s34, 0x110
	v_or_b32_e32 v182, 28, v3
	v_bitop3_b32 v2, v2, 7, s33 bitop3:0xc8
	v_lshlrev_b32_e32 v150, 3, v6
	v_mul_u32_u24_e32 v7, 0x48, v151
	v_lshlrev_b32_e32 v170, 2, v6
	v_lshl_add_u64 v[152:153], v[0:1], 0, s[18:19]
	s_movk_i32 s17, 0x90
	v_or_b32_e32 v0, 0x3f00, v5
	v_mul_u32_u24_e32 v1, 0x110, v175
	v_mul_lo_u32 v5, v178, s34
	v_mul_lo_u32 v3, v182, s34
	v_lshlrev_b32_e32 v158, 4, v2
	v_lshlrev_b32_e32 v2, 11, v151
	v_ashrrev_i32_e32 v149, 31, v148
	v_mul_lo_u32 v171, v147, s17
	s_mov_b32 s17, s16
	s_mov_b32 s18, s16
	s_mov_b32 s19, s16
	s_mov_b32 s20, s16
	s_mov_b32 s21, s16
	s_mov_b32 s22, s16
	s_mov_b32 s23, s16
	s_mov_b32 s24, s16
	s_mov_b32 s25, s16
	s_mov_b32 s26, s16
	s_mov_b32 s27, s16
	s_mov_b32 s28, s16
	s_mov_b32 s29, s16
	s_mov_b32 s30, s16
	s_mov_b32 s31, s16
	v_add_u32_e32 v173, v4, v8
	v_add3_u32 v174, v9, v10, v150
	v_or_b32_e32 v176, 4, v175
	v_or_b32_e32 v177, 8, v175
	v_or_b32_e32 v179, 16, v175
	v_or_b32_e32 v180, 20, v175
	v_or_b32_e32 v181, 24, v175
	v_mov_b32_e32 v156, v145
	v_mov_b32_e32 v157, v145
	v_sub_u32_e32 v183, v167, v170
	v_mov_b32_e32 v159, v209
	s_lshl_b32 s58, s53, 1
	v_lshlrev_b32_e32 v160, 1, v146
	v_lshlrev_b32_e32 v184, 1, v2
	v_lshlrev_b32_e32 v185, 1, v7
	v_add_u32_e32 v186, v4, v0
	v_add_u32_e32 v187, v11, v1
	v_add_u32_e32 v188, v11, v5
	v_add_u32_e32 v189, v11, v3
	s_branch .LBB0_740

.LBB0_764:
	s_setprio 0
	s_or_b64 exec, exec, s[4:5]
	s_barrier
	s_load_dwordx2 s[8:9], s[0:1], 0x148
	v_mbcnt_lo_u32_b32 v11, -1, 0
	v_mbcnt_hi_u32_b32 v11, -1, v11
	s_and_b64 vcc, exec, s[12:13]
	v_or_b32_e32 v0, s33, v11
	s_nop 0
	v_readfirstlane_b32 s34, v0
	s_cbranch_vccnz .LBB0_796
	v_lshlrev_b32_e32 v1, 4, v0
	v_add_u32_e32 v2, 0x2000, v1
	v_ashrrev_i32_e32 v3, 31, v2
	v_lshrrev_b32_e32 v3, 22, v3
	v_add_u32_e32 v3, v2, v3
	v_ashrrev_i32_e32 v8, 10, v3
	v_mul_i32_i24_e32 v3, 0x400, v8
	v_sub_u32_e32 v2, v2, v3
	v_lshrrev_b32_e32 v3, 4, v2
	v_bitop3_b32 v2, v3, v2, 32 bitop3:0x6c
	v_ashrrev_i32_e32 v3, 31, v2
	v_lshrrev_b32_e32 v3, 26, v3
	v_add_u32_e32 v3, v2, v3
	v_lshlrev_b32_e32 v4, 3, v8
	v_ashrrev_i32_e32 v9, 6, v3
	v_and_b32_e32 v4, -16, v4
	v_add_u32_e32 v4, v9, v4
	v_and_b32_e32 v5, 3, v9
	v_lshrrev_b32_e32 v6, 2, v4
	v_lshlrev_b32_e32 v7, 1, v4
	v_and_b32_e32 v3, 0xc0, v3
	v_and_or_b32 v5, v4, s86, v5
	v_and_b32_e32 v6, 4, v6
	v_and_b32_e32 v7, 24, v7
	v_sub_u32_e32 v2, v2, v3
	v_or3_b32 v5, v5, v6, v7
	v_lshlrev_b32_e32 v6, 5, v8
	v_ashrrev_i16_sdwa v2, v250, sext(v2) dst_sel:DWORD dst_unused:UNUSED_PAD src0_sel:DWORD src1_sel:BYTE_0
	v_and_b32_e32 v6, 32, v6
	v_bfe_i32 v10, v2, 0, 16
	v_add_lshl_u32 v2, v6, v10, 1
	s_waitcnt vmcnt(3)
	v_lshl_add_u32 v128, v5, 11, v2
	v_lshl_add_u32 v130, v4, 11, v2
	v_bfe_i32 v2, v0, 27, 1
	v_lshrrev_b32_e32 v2, 22, v2
	v_add_u32_e32 v2, v1, v2
	v_and_b32_e32 v2, 0xfffffc00, v2
	v_sub_u32_e32 v1, v1, v2
	v_lshrrev_b32_e32 v2, 4, v1
	v_ashrrev_i32_e32 v3, 31, v0
	v_bitop3_b32 v1, v2, v1, 32 bitop3:0x6c
	v_lshrrev_b32_e32 v3, 26, v3
	v_ashrrev_i32_e32 v2, 31, v1
	v_add_u32_e32 v0, v0, v3
	v_lshrrev_b32_e32 v2, 26, v2
	v_ashrrev_i32_e32 v13, 6, v0
	v_add_u32_e32 v2, v1, v2
	v_lshlrev_b32_e32 v0, 3, v13
	s_waitcnt lgkmcnt(0)
	s_add_u32 s35, s8, 0x2a000000
	v_ashrrev_i32_e32 v12, 6, v2
	v_and_b32_e32 v0, -16, v0
	s_addc_u32 s46, s9, 0
	v_add_u32_e32 v0, v12, v0
	s_add_u32 s50, s8, 0xfe0000
	v_and_b32_e32 v3, 3, v12
	v_lshrrev_b32_e32 v4, 2, v0
	v_lshlrev_b32_e32 v5, 1, v0
	v_and_b32_e32 v2, 0xc0, v2
	s_addc_u32 s51, s9, 0
	s_ashr_i32 s5, s34, 6
	v_and_or_b32 v3, v0, s86, v3
	v_and_b32_e32 v4, 4, v4
	v_and_b32_e32 v5, 24, v5
	v_sub_u32_e32 v1, v1, v2
	s_ashr_i32 s4, s34, 8
	s_lshl_b32 s53, s5, 10
	v_or3_b32 v3, v3, v4, v5
	v_lshlrev_b32_e32 v4, 5, v13
	v_ashrrev_i16_sdwa v1, v250, sext(v1) dst_sel:DWORD dst_unused:UNUSED_PAD src0_sel:DWORD src1_sel:BYTE_0
	v_and_b32_e32 v4, 32, v4
	v_bfe_i32 v14, v1, 0, 16
	s_add_u32 s28, s50, s94
	v_add_lshl_u32 v1, v4, v14, 1
	s_addc_u32 s29, s51, 0
	s_add_i32 s54, s53, 0
	v_lshl_add_u32 v208, v3, 11, v1
	s_add_i32 m0, s54, 0x10000
	s_waitcnt vmcnt(2)
	v_lshl_add_u32 v132, v0, 11, v1
	global_load_lds_dwordx4 v208, s[28:29]
	s_add_i32 m0, s54, 0x12000
	s_add_u32 s26, s35, s81
	global_load_lds_dwordx4 v128, s[28:29]
	s_addc_u32 s27, s46, 0
	s_mov_b32 m0, s54
	s_add_i32 s55, s54, 0x2000
	global_load_lds_dwordx4 v132, s[26:27]
	s_mov_b32 m0, s55
	s_add_u32 s6, s28, 0x40000
	global_load_lds_dwordx4 v130, s[26:27]
	s_addc_u32 s7, s29, 0
	s_add_i32 m0, s54, 0x14000
	v_mov_b32_e32 v129, v209
	global_load_lds_dwordx4 v208, s[6:7]
	s_add_i32 m0, s54, 0x16000
	v_mov_b32_e32 v133, v209
	global_load_lds_dwordx4 v128, s[6:7]
	s_add_u32 s6, s26, 0x40000
	s_addc_u32 s7, s27, 0
	s_add_i32 s56, s54, 0x4000
	s_mov_b32 m0, s56
	s_add_i32 s57, s54, 0x6000
	global_load_lds_dwordx4 v132, s[6:7]
	s_mov_b32 m0, s57
	v_mov_b32_e32 v131, v209
	global_load_lds_dwordx4 v130, s[6:7]
	v_lshl_add_u64 v[6:7], s[28:29], 0, v[208:209]
	v_lshl_add_u64 v[4:5], s[28:29], 0, v[128:129]
	v_lshl_add_u64 v[2:3], s[26:27], 0, v[132:133]
	s_cmp_lg_u32 s4, 1
	v_lshl_add_u64 v[0:1], s[26:27], 0, v[130:131]
	s_cbranch_scc1 .LBB0_767
	s_barrier

.LBB0_844:
	v_lshlrev_b32_e32 v12, 4, v0
	global_load_dwordx4 v[4:7], v12, s[14:15]
	global_load_dwordx4 v[8:11], v12, s[16:17]
	s_waitcnt vmcnt(0)
	v_max3_f32 v2, |v4|, |v5|, |v6|
	v_max3_f32 v1, |v8|, |v9|, |v10|
	v_max_f32_e64 v2, v2, |v7|
	v_max_f32_e64 v1, v1, |v11|
	s_nop 1
	v_max_f32_dpp v2, v2, v2 quad_perm:[1,0,3,2] row_mask:0xf bank_mask:0xf
	v_max_f32_dpp v1, v1, v1 quad_perm:[1,0,3,2] row_mask:0xf bank_mask:0xf
	s_nop 1
	v_max_f32_dpp v2, v2, v2 quad_perm:[2,3,0,1] row_mask:0xf bank_mask:0xf
	v_max_f32_dpp v1, v1, v1 quad_perm:[2,3,0,1] row_mask:0xf bank_mask:0xf
	s_nop 1
	v_max_f32_dpp v2, v2, v2 row_half_mirror row_mask:0xf bank_mask:0xf
	v_max_f32_dpp v1, v1, v1 row_half_mirror row_mask:0xf bank_mask:0xf
	s_nop 1
	v_max_f32_dpp v2, v2, v2 row_mirror row_mask:0xf bank_mask:0xf
	v_max_f32_dpp v1, v1, v1 row_mirror row_mask:0xf bank_mask:0xf
	v_mov_b32_e32 v13, v2
	v_mov_b32_e32 v14, v1
	s_nop 1
	v_permlane16_swap_b32_e32 v2, v13
	v_permlane16_swap_b32_e32 v1, v14
	s_nop 0
	v_max_f32_e32 v2, v2, v13
	v_max_f32_e32 v1, v1, v14
	v_mov_b32_e32 v13, v2
	v_mov_b32_e32 v14, v1
	s_nop 1
	v_permlane32_swap_b32_e32 v2, v13
	v_permlane32_swap_b32_e32 v1, v14
	s_nop 0
	v_max_f32_e32 v2, v2, v13
	v_max_f32_e32 v1, v1, v14
	v_mul_f32_e32 v2, 0x41b8aa3b, v2
	v_mul_f32_e32 v1, v1, v2
	s_mov_b32 s47, s2
	s_cmpk_gt_i32 s47, 0x7ff
	v_readfirstlane_b32 s16, v1
	s_cbranch_scc1 .LBB0_851
	s_lshl_b32 s6, s52, 24
	s_add_u32 s14, s10, 0x12000000
	s_addc_u32 s15, s11, 0
	s_add_u32 s17, s10, s6
	s_addc_u32 s18, s11, 0
	s_add_u32 s56, s17, 0x6800000
	s_addc_u32 s57, s18, 0
	v_and_b32_e32 v9, 64, v252
	s_add_u32 s58, s17, 0x4800000
	v_xor_b32_e32 v8, 32, v252
	v_add_u32_e32 v9, 64, v9
	v_or_b32_e32 v1, s33, v0
	s_addc_u32 s59, s18, 0
	s_lshl_b32 s36, s52, 8
	v_cmp_lt_i32_e32 vcc, v8, v9
	v_bfe_u32 v5, v0, 5, 1
	v_and_b32_e32 v7, 31, v0
	v_ashrrev_i32_e32 v6, 2, v1
	s_movk_i32 s17, 0xffe0
	v_cndmask_b32_e32 v8, v252, v8, vcc
	s_lshl_b64 s[18:19], s[36:37], 2
	v_ashrrev_i32_e32 v3, 6, v1
	v_and_b32_e32 v200, 0xffffffe0, v6
	v_bfi_b32 v207, s17, v6, v0
	v_lshlrev_b32_e32 v6, 3, v5
	v_lshlrev_b32_e32 v215, 2, v8
	s_add_u32 s4, s4, s18
	v_mul_u32_u24_e32 v8, 0x210, v7
	v_lshlrev_b32_e32 v5, 4, v5
	s_addc_u32 s5, s5, s19
	v_and_b32_e32 v208, 32, v0
	v_add3_u32 v228, 0, v8, v5
	v_lshlrev_b32_e32 v5, 7, v3
	v_lshl_add_u64 v[202:203], s[4:5], 0, v[208:209]
	s_cmp_ge_u32 s33, 0x100
	s_cbranch_scc0 .Lprio_xa
	s_setprio 1
.Lprio_xa:
	v_lshlrev_b32_e32 v14, 4, v252
	global_load_dwordx4 v[10:13], v14, s[4:5]
	v_add_u32_e32 v14, 0x1f000, v14
	v_add_u32_e32 v202, 0x1f000, v208
	s_waitcnt vmcnt(0)
	ds_write_b128 v14, v[10:13]
	s_waitcnt lgkmcnt(0)
	s_barrier
	v_and_b32_e32 v5, 0x80, v5
	s_movk_i32 s4, 0x2200
	v_ashrrev_i32_e32 v196, 3, v1
	v_ashrrev_i32_e32 v198, 5, v1
	v_lshlrev_b32_e32 v4, 3, v1
	v_mul_lo_u32 v3, v3, s4
	v_lshlrev_b32_e32 v1, 4, v1
	v_lshlrev_b32_e32 v208, 1, v5
	v_add_u32_e32 v3, 0, v3
	s_movk_i32 s4, 0x110
	v_and_b32_e32 v8, 0xf0, v1
	v_lshl_add_u64 v[10:11], s[10:11], 0, v[208:209]
	v_mov_b32_e32 v9, v209
	v_ashrrev_i32_e32 v199, 31, v198
	v_or_b32_e32 v14, v5, v7
	v_mad_u32_u24 v7, v7, s4, v3
	v_add_u32_e32 v1, v3, v8
	v_lshl_add_u64 v[8:9], v[10:11], 0, v[8:9]
	s_mov_b64 s[4:5], 0x2a000000
	v_lshl_add_u64 v[204:205], v[8:9], 0, s[4:5]
	v_mul_u32_u24_e32 v5, 0x90, v14
	v_lshlrev_b64 v[8:9], 11, v[198:199]
	v_bitop3_b32 v14, v0, 31, s33 bitop3:0xc8
	v_bfe_u32 v206, v0, 4, 2
	s_movk_i32 s4, 0x210
	v_lshl_or_b32 v8, v14, 4, v8
	v_ashrrev_i32_e32 v197, 31, v196
	v_and_b32_e32 v2, 56, v4
	v_and_b32_e32 v4, 0xf8, v4
	v_add3_u32 v229, 0, v5, v6
	v_mul_lo_u32 v5, v198, s4
	s_movk_i32 s4, 0x90
	v_or_b32_e32 v214, 4, v206
	v_lshl_add_u64 v[216:217], s[10:11], 0, v[8:9]
	v_lshlrev_b64 v[8:9], 14, v[196:197]
	v_bitop3_b32 v0, v0, 7, s33 bitop3:0xc8
	v_lshl_add_u32 v12, v4, 1, 0
	v_lshl_add_u32 v13, v2, 1, 0
	s_xor_b32 s16, s16, 0x80000000
	v_mul_u32_u24_e32 v3, 0x110, v206
	v_mul_lo_u32 v10, v196, s4
	v_mul_u32_u24_e32 v11, 0x110, v214
	v_lshl_or_b32 v8, v0, 4, v8
	s_mov_b32 s7, s37
	v_ashrrev_i32_e32 v201, 31, v200
	s_mov_b32 s17, s16
	s_mov_b32 s18, s16
	s_mov_b32 s19, s16
	s_mov_b32 s20, s16
	s_mov_b32 s21, s16
	s_mov_b32 s22, s16
	s_mov_b32 s23, s16
	s_mov_b32 s24, s16
	s_mov_b32 s25, s16
	s_mov_b32 s26, s16
	s_mov_b32 s27, s16
	s_mov_b32 s28, s16
	s_mov_b32 s29, s16
	s_mov_b32 s30, s16
	s_mov_b32 s31, s16
	s_lshl_b32 s53, s47, 4
	v_lshl_add_u64 v[218:219], s[10:11], 0, v[8:9]
	v_lshlrev_b32_e32 v208, 1, v4
	v_lshlrev_b32_e32 v220, 1, v2
	v_lshlrev_b32_e32 v222, 1, v6
	v_add_u32_e32 v197, v7, v6
	v_add_u32_e32 v230, v1, v3
	v_add_u32_e32 v231, v1, v11
	v_add_u32_e32 v232, v12, v5
	v_add_u32_e32 v233, v13, v10

.LBB0_851:
	s_setprio 0
	s_waitcnt vmcnt(0)
	s_barrier
	v_mbcnt_lo_u32_b32 v0, -1, 0
	v_mbcnt_hi_u32_b32 v0, -1, v0
	s_nop 0
	v_or_b32_e32 v0, s33, v0
	v_cmp_eq_u32_e32 vcc, 0, v0
	s_and_saveexec_b64 s[4:5], vcc
	s_cbranch_execz .LBB0_866
	s_lshl_b32 s6, s43, 2
	s_mov_b64 s[14:15], exec
	s_add_u32 s6, s10, s6
	s_addc_u32 s7, s11, 0
	v_mbcnt_lo_u32_b32 v0, s14, 0
	s_add_u32 s6, s6, 0x9800000
	v_mbcnt_hi_u32_b32 v0, s15, v0
	s_addc_u32 s7, s7, 0
	v_cmp_eq_u32_e32 vcc, 0, v0
	s_and_saveexec_b64 s[16:17], vcc
	s_cbranch_execz .LBB0_854
	s_bcnt1_i32_b64 s14, s[14:15]
	v_mov_b32_e32 v1, s14
	global_atomic_add v1, v209, v1, s[6:7] sc0
